# v22 + grid barrier before the split-K sum replaced by a completion counter: part units store write-through and count arrivals; workgroups without a part unit wait for the count, acquire and do the sum
# baseline (speedup 1.0000x reference)
;     __device__ __forceinline__ void operator()(const f32x4 (&acc)[2][2][4][2], const Unit& u, int wr, int wc, int fr, int fq) const {
;     ...
;         if (u.pm >= 64) {
; #pragma unroll
;             for (int ai = 0; ai < 2; ++ai)
; #pragma unroll
;                 for (int m = 0; m < 4; ++m)
; #pragma unroll
;                     for (int bj = 0; bj < 2; ++bj) { float* pp = part + ((size_t)(u.kb >> 9) * 512 + (row0 - MPR + ai * HALF + m * 16)) * 1024 + col0 + bj * HALF;
;                         *(f32x4*)pp = acc[ai][bj][m][0]; *(f32x4*)(pp + 4) = acc[ai][bj][m][1]; }
;             return; }
.LBB0_1184:
	s_add_u32 s44, s58, s44
	v_ashrrev_i32_e32 v151, 31, v150
	s_addc_u32 s45, s59, s45
	v_lshlrev_b64 v[130:131], 12, v[150:151]
	v_ashrrev_i32_e32 v153, 31, v152
	v_lshl_add_u64 v[130:131], s[44:45], 0, v[130:131]
	v_lshl_add_u64 v[130:131], v[152:153], 2, v[130:131]
	v_add_co_u32_e32 v134, vcc, 0xfc000000, v130
	v_lshl_add_u64 v[132:133], v[130:131], 0, s[26:27]
	s_nop 0
	v_addc_co_u32_e32 v135, vcc, -1, v131, vcc
	global_store_dwordx4 v[134:135], v[126:129], off sc1
	global_store_dwordx4 v[132:133], v[122:125], off offset:16 sc1
	global_store_dwordx4 v[132:133], v[110:113], off offset:512 sc1
	global_store_dwordx4 v[132:133], v[102:105], off offset:528 sc1
	s_nop 1
	v_add_co_u32_e32 v104, vcc, 0xfc010000, v130
	v_lshl_add_u64 v[102:103], v[130:131], 0, s[28:29]
	s_nop 0
	v_addc_co_u32_e32 v105, vcc, -1, v131, vcc
	global_store_dwordx4 v[104:105], v[118:121], off sc1
	global_store_dwordx4 v[102:103], v[114:117], off offset:16 sc1
	global_store_dwordx4 v[102:103], v[94:97], off offset:512 sc1
	global_store_dwordx4 v[102:103], v[86:89], off offset:528 sc1
	s_nop 1
	v_add_co_u32_e32 v88, vcc, 0xfc020000, v130
	v_lshl_add_u64 v[86:87], v[130:131], 0, s[30:31]
	s_nop 0
	v_addc_co_u32_e32 v89, vcc, -1, v131, vcc
	global_store_dwordx4 v[88:89], v[106:109], off sc1
	global_store_dwordx4 v[86:87], v[98:101], off offset:16 sc1
	global_store_dwordx4 v[86:87], v[78:81], off offset:512 sc1
	global_store_dwordx4 v[86:87], v[74:77], off offset:528 sc1
	s_nop 1
	v_add_co_u32_e32 v76, vcc, 0xfc030000, v130
	v_lshl_add_u64 v[74:75], v[130:131], 0, s[34:35]
	s_nop 0
	v_addc_co_u32_e32 v77, vcc, -1, v131, vcc
	global_store_dwordx4 v[76:77], v[90:93], off sc1
	global_store_dwordx4 v[74:75], v[82:85], off offset:16 sc1
	global_store_dwordx4 v[74:75], v[70:73], off offset:512 sc1
	global_store_dwordx4 v[74:75], v[66:69], off offset:528 sc1
	s_nop 1
	v_add_co_u32_e32 v68, vcc, 0xfc080000, v130
	v_lshl_add_u64 v[66:67], v[130:131], 0, s[36:37]
	s_nop 0
	v_addc_co_u32_e32 v69, vcc, -1, v131, vcc
	global_store_dwordx4 v[68:69], v[62:65], off sc1
	global_store_dwordx4 v[66:67], v[58:61], off offset:16 sc1
	global_store_dwordx4 v[66:67], v[46:49], off offset:512 sc1
	global_store_dwordx4 v[66:67], v[38:41], off offset:528 sc1
	s_nop 1
	v_add_co_u32_e32 v40, vcc, 0xfc090000, v130
	v_lshl_add_u64 v[38:39], v[130:131], 0, s[38:39]
	s_nop 0
	v_addc_co_u32_e32 v41, vcc, -1, v131, vcc
	global_store_dwordx4 v[40:41], v[54:57], off sc1
	global_store_dwordx4 v[38:39], v[50:53], off offset:16 sc1
	global_store_dwordx4 v[38:39], v[30:33], off offset:512 sc1
	global_store_dwordx4 v[38:39], v[22:25], off offset:528 sc1
	s_nop 1
	v_add_co_u32_e32 v24, vcc, 0xfc0a0000, v130
	v_lshl_add_u64 v[22:23], v[130:131], 0, s[40:41]
	s_nop 0
	v_addc_co_u32_e32 v25, vcc, -1, v131, vcc
	global_store_dwordx4 v[24:25], v[42:45], off sc1
	global_store_dwordx4 v[22:23], v[34:37], off offset:16 sc1
	global_store_dwordx4 v[22:23], v[14:17], off offset:512 sc1
	global_store_dwordx4 v[22:23], v[10:13], off offset:528 sc1
	s_nop 1
	v_add_co_u32_e32 v12, vcc, 0xfc0b0000, v130
	v_lshl_add_u64 v[10:11], v[130:131], 0, s[42:43]
	s_nop 0
	v_addc_co_u32_e32 v13, vcc, -1, v131, vcc
	global_store_dwordx4 v[12:13], v[26:29], off sc1
	global_store_dwordx4 v[10:11], v[18:21], off offset:16 sc1
	global_store_dwordx4 v[10:11], v[6:9], off offset:512 sc1
	global_store_dwordx4 v[10:11], v[2:5], off offset:528 sc1
	s_waitcnt vmcnt(0)
	s_mov_b64 s[100:101], exec
	s_mov_b64 exec, 1
	v_readlane_b32 s98, v255, 4
	v_readlane_b32 s99, v255, 5
	s_add_u32 s98, s98, 0x2300
	s_addc_u32 s99, s99, 0
	v_mov_b32_e32 v130, 0
	v_mov_b32_e32 v131, 1
	global_atomic_add v130, v131, s[98:99]
	s_mov_b64 exec, s[100:101]
	s_and_b64 vcc, exec, s[4:5]
	s_mov_b64 s[62:63], -1
	s_cbranch_vccnz .LBB0_1171

; __device__ __forceinline__ KArgs kargs() { KArgs p = (KArgs)__builtin_amdgcn_kernarg_segment_ptr(); asm volatile("" : "+s"(p)); return p; }
; #define TSTAMP(i) do { if (bx == 0 && tid == 0) ((volatile LAS unsigned*)(lds + MISC_OFF))[16 + (i)] = (unsigned)__builtin_amdgcn_s_memrealtime(); } while (0)
; #define TSTAMP(i) do {} while (0)
; __global__ void __launch_bounds__(NWAVES * 64, 2) fwd(Args args_unused) {
;     ...
;     xcd_barrier(bar);
;     TSTAMP(10);
;     { KArgs A = kargs(); const float* part = (const float*)(A->ws + WS_PART); float* ys = A->out + O_YS; const bf16* x1b = (const bf16*)(A->ws + WS_X1B);
;       int g8_ = G, t8_ = threadIdx.x, v8_ = vcu; asm volatile("" : "+s"(g8_), "+s"(v8_)); asm volatile("" : "+v"(t8_));
; #pragma nounroll
;       for (int e4 = (v8_ * (NWAVES * 64) + t8_); e4 < MS * DM / 4; e4 += g8_ * NWAVES * 64) {
;         const v2u xw = *(const v2u*)(x1b + (size_t)MP * DM + (size_t)e4 * 4);
;         f32x4 s = {__builtin_bit_cast(float, xw.x << 16), __builtin_bit_cast(float, xw.x & 0xffff0000u), __builtin_bit_cast(float, xw.y << 16), __builtin_bit_cast(float, xw.y & 0xffff0000u)};
; #pragma unroll
;         for (int p = 0; p < 11; ++p) s += *(const f32x4*)(part + (size_t)p * MS * DM + (size_t)e4 * 4);
;         *(f32x4*)(ys + (size_t)e4 * 4) = s; }
.LBB0_1188:
	s_waitcnt vmcnt(0)
	v_readlane_b32 s46, v255, 11
	s_and_b32 s0, s46, 31
	s_cmp_lt_u32 s0, 11
	s_cbranch_scc1 .LBB0_1244
	v_readlane_b32 s2, v255, 4
	v_readlane_b32 s3, v255, 5
	s_add_u32 s2, s2, 0x2300
	s_addc_u32 s3, s3, 0
	v_mov_b32_e32 v1, 0
	s_mov_b32 s1, 0
.Lp8_poll:
	global_load_dword v2, v1, s[2:3] sc1
	s_waitcnt vmcnt(0)
	v_readfirstlane_b32 s4, v2
	s_cmpk_gt_u32 s4, 0x2bf
	s_cbranch_scc1 .Lp8_go
	s_sleep 2
	s_add_i32 s1, s1, 1
	s_cmp_lt_u32 s1, 0x40000
	s_cbranch_scc1 .Lp8_poll
.Lp8_go:
	buffer_inv sc1
	s_waitcnt vmcnt(0)
	s_lshr_b32 s4, s46, 5
	s_mul_i32 s4, s4, 21
	s_add_i32 s4, s4, s0
	s_add_i32 s46, s4, -11
	s_movk_i32 s52, 0xa8
	s_mov_b32 s0, 0x20000
	v_lshl_add_u32 v0, s46, 9, v0
	v_cmp_gt_i32_e32 vcc, s0, v0
	s_and_saveexec_b64 s[0:1], vcc
	s_cbranch_execz .LBB0_1244
	s_load_dwordx4 s[4:7], s[56:57], 0xb0
	v_ashrrev_i32_e32 v1, 31, v0
	s_mov_b64 s[8:9], 0x11400000
	v_lshlrev_b64 v[2:3], 4, v[0:1]
	s_mov_b64 s[10:11], 0
	s_waitcnt lgkmcnt(0)
	s_add_u32 s0, s4, 0x4000000
	s_addc_u32 s1, s5, 0
	s_lshl_b32 s2, s52, 9
	v_lshl_add_u64 v[4:5], v[0:1], 3, s[6:7]
	s_ashr_i32 s3, s2, 31
	s_lshl_b64 s[4:5], s[2:3], 4
	v_lshl_add_u64 v[4:5], v[4:5], 0, s[8:9]
	s_lshl_b64 s[8:9], s[2:3], 3
	s_mov_b32 s3, 0x1ffff
